# c9 + attention softmax: per-lane max via four v_max3 chains (no canonicalising v_max x,x), exp argument via one fma instead of sub+mul
# speedup vs baseline: 1.0037x; 1.0009x over previous
; __device__ __forceinline__ f32x4 mfma16(bf16x8 a, bf16x8 b, f32x4 c) { return __builtin_amdgcn_mfma_f32_16x16x32_bf16(a, b, c, 0, 0, 0); }
; __device__ __forceinline__ void phase_attn(const Args& a, unsigned char* smem, int tid, int lane, int wave, bf16_t* Yout) {
;     ...
; #pragma unroll
;             for (int c = 0; c < 8; ++c)
; #pragma unroll
;                 for (int hf = 0; hf < 2; ++hf) {
;                     const bf16_t* kp = Ks + (c * 32 + wo + 4 * hf) * 72 + 8 * g;
;                     const bf16x8 k0 = *(const bf16x8*)kp, k1 = *(const bf16x8*)(kp + 32);
;                     f32x4 s = {0.f, 0.f, 0.f, 0.f};
;                     s = mfma16(k0, qf0, s); s = mfma16(k1, qf1, s);
;                     st[16 + c * 2 + hf] = s * 0.125f;
;                 }
.LBB0_334:
	s_or_b64 exec, exec, s[22:23]
	ds_read_b128 v[8:11], v182
	ds_read_b128 v[12:15], v182 offset:64
	v_lshlrev_b32_e32 v114, 1, v114
	s_lshl_b32 s12, s12, 1
	s_add_i32 s53, s53, 2
	s_waitcnt lgkmcnt(1)
	v_mfma_f32_16x16x32_bf16 v[8:11], v[8:11], v[4:7], 0
	s_add_i32 s54, s54, -2
	s_add_i32 s66, s66, 8
	s_addk_i32 s55, 0x80
	s_waitcnt lgkmcnt(0)
	v_mfma_f32_16x16x32_bf16 v[8:11], v[12:15], v[0:3], v[8:11]
	s_cmpk_gt_u32 s66, 0x77
	s_nop 6
	v_pk_mul_f32 v[60:61], v[10:11], s[18:19] op_sel_hi:[1,0]
	v_pk_mul_f32 v[66:67], v[8:9], s[18:19] op_sel_hi:[1,0]
	ds_read_b128 v[8:11], v182 offset:576
	ds_read_b128 v[12:15], v182 offset:640
	s_waitcnt lgkmcnt(1)
	v_mfma_f32_16x16x32_bf16 v[8:11], v[8:11], v[4:7], 0
	s_waitcnt lgkmcnt(0)
	v_mfma_f32_16x16x32_bf16 v[8:11], v[12:15], v[0:3], v[8:11]
	s_nop 7
	v_pk_mul_f32 v[56:57], v[10:11], s[18:19] op_sel_hi:[1,0]
	v_pk_mul_f32 v[64:65], v[8:9], s[18:19] op_sel_hi:[1,0]
	ds_read_b128 v[8:11], v182 offset:4608
	ds_read_b128 v[12:15], v182 offset:4672
	s_waitcnt lgkmcnt(1)
	v_mfma_f32_16x16x32_bf16 v[8:11], v[8:11], v[4:7], 0
	s_waitcnt lgkmcnt(0)
	v_mfma_f32_16x16x32_bf16 v[8:11], v[12:15], v[0:3], v[8:11]
	s_nop 7
	v_pk_mul_f32 v[50:51], v[10:11], s[18:19] op_sel_hi:[1,0]
	v_pk_mul_f32 v[62:63], v[8:9], s[18:19] op_sel_hi:[1,0]
	ds_read_b128 v[8:11], v182 offset:5184
	ds_read_b128 v[12:15], v182 offset:5248
	s_waitcnt lgkmcnt(1)
	v_mfma_f32_16x16x32_bf16 v[8:11], v[8:11], v[4:7], 0
	s_waitcnt lgkmcnt(0)
	v_mfma_f32_16x16x32_bf16 v[8:11], v[12:15], v[0:3], v[8:11]
	s_nop 7
	v_pk_mul_f32 v[42:43], v[10:11], s[18:19] op_sel_hi:[1,0]
	v_pk_mul_f32 v[52:53], v[8:9], s[18:19] op_sel_hi:[1,0]
	ds_read_b128 v[8:11], v182 offset:9216
	ds_read_b128 v[12:15], v182 offset:9280
	s_waitcnt lgkmcnt(1)
	v_mfma_f32_16x16x32_bf16 v[8:11], v[8:11], v[4:7], 0
	s_waitcnt lgkmcnt(0)
	v_mfma_f32_16x16x32_bf16 v[8:11], v[12:15], v[0:3], v[8:11]
	s_nop 7
	v_pk_mul_f32 v[36:37], v[10:11], s[18:19] op_sel_hi:[1,0]
	v_pk_mul_f32 v[46:47], v[8:9], s[18:19] op_sel_hi:[1,0]
	ds_read_b128 v[8:11], v182 offset:9792
	ds_read_b128 v[12:15], v182 offset:9856
	s_waitcnt lgkmcnt(1)
	v_mfma_f32_16x16x32_bf16 v[8:11], v[8:11], v[4:7], 0
	s_waitcnt lgkmcnt(0)
	v_mfma_f32_16x16x32_bf16 v[8:11], v[12:15], v[0:3], v[8:11]
	s_nop 7
	v_pk_mul_f32 v[30:31], v[10:11], s[18:19] op_sel_hi:[1,0]
	v_pk_mul_f32 v[40:41], v[8:9], s[18:19] op_sel_hi:[1,0]
	ds_read_b128 v[8:11], v182 offset:13824
	ds_read_b128 v[12:15], v182 offset:13888
	s_waitcnt lgkmcnt(1)
	v_mfma_f32_16x16x32_bf16 v[8:11], v[8:11], v[4:7], 0
	s_waitcnt lgkmcnt(0)
	v_mfma_f32_16x16x32_bf16 v[8:11], v[12:15], v[0:3], v[8:11]
	s_nop 7
	v_pk_mul_f32 v[24:25], v[10:11], s[18:19] op_sel_hi:[1,0]
	v_pk_mul_f32 v[34:35], v[8:9], s[18:19] op_sel_hi:[1,0]
	ds_read_b128 v[8:11], v182 offset:14400
	ds_read_b128 v[12:15], v182 offset:14464
	s_waitcnt lgkmcnt(1)
	v_mfma_f32_16x16x32_bf16 v[8:11], v[8:11], v[4:7], 0
	s_waitcnt lgkmcnt(0)
	v_mfma_f32_16x16x32_bf16 v[8:11], v[12:15], v[0:3], v[8:11]
	s_nop 7
	v_pk_mul_f32 v[16:17], v[10:11], s[18:19] op_sel_hi:[1,0]
	v_pk_mul_f32 v[28:29], v[8:9], s[18:19] op_sel_hi:[1,0]
	ds_read_b128 v[8:11], v182 offset:18432
	ds_read_b128 v[12:15], v182 offset:18496
	s_waitcnt lgkmcnt(1)
	v_mfma_f32_16x16x32_bf16 v[8:11], v[8:11], v[4:7], 0
	s_waitcnt lgkmcnt(0)
	v_mfma_f32_16x16x32_bf16 v[8:11], v[12:15], v[0:3], v[8:11]
	s_nop 7
	v_pk_mul_f32 v[12:13], v[10:11], s[18:19] op_sel_hi:[1,0]
	v_pk_mul_f32 v[22:23], v[8:9], s[18:19] op_sel_hi:[1,0]
	ds_read_b128 v[8:11], v182 offset:19008
	ds_read_b128 v[18:21], v182 offset:19072
	s_waitcnt lgkmcnt(1)
	v_mfma_f32_16x16x32_bf16 v[8:11], v[8:11], v[4:7], 0
	s_waitcnt lgkmcnt(0)
	v_mfma_f32_16x16x32_bf16 v[18:21], v[18:21], v[0:3], v[8:11]
	s_nop 7
	v_pk_mul_f32 v[8:9], v[20:21], s[18:19] op_sel_hi:[1,0]
	v_pk_mul_f32 v[14:15], v[18:19], s[18:19] op_sel_hi:[1,0]
	ds_read_b128 v[18:21], v182 offset:23040
	ds_read_b128 v[184:187], v182 offset:23104
	s_waitcnt lgkmcnt(1)
	v_mfma_f32_16x16x32_bf16 v[18:21], v[18:21], v[4:7], 0
	s_waitcnt lgkmcnt(0)
	v_mfma_f32_16x16x32_bf16 v[18:21], v[184:187], v[0:3], v[18:21]
	ds_read_b128 v[184:187], v182 offset:23616
	ds_read_b128 v[188:191], v182 offset:23680
	s_waitcnt lgkmcnt(1)
	v_mfma_f32_16x16x32_bf16 v[184:187], v[184:187], v[4:7], 0
	s_nop 3
	v_mul_f32_e64 v10, v20, s18
	v_mul_f32_e64 v11, v21, s18
	v_pk_mul_f32 v[20:21], v[18:19], s[18:19] op_sel_hi:[1,0]
	s_waitcnt lgkmcnt(0)
	v_mfma_f32_16x16x32_bf16 v[184:187], v[188:191], v[0:3], v[184:187]
	s_nop 7
	v_pk_mul_f32 v[18:19], v[186:187], s[18:19] op_sel_hi:[1,0]
	v_pk_mul_f32 v[32:33], v[184:185], s[18:19] op_sel_hi:[1,0]
	ds_read_b128 v[184:187], v182 offset:27648
	ds_read_b128 v[188:191], v182 offset:27712
	s_waitcnt lgkmcnt(1)
	v_mfma_f32_16x16x32_bf16 v[184:187], v[184:187], v[4:7], 0
	s_waitcnt lgkmcnt(0)
	v_mfma_f32_16x16x32_bf16 v[184:187], v[188:191], v[0:3], v[184:187]
	s_nop 7
	v_pk_mul_f32 v[26:27], v[186:187], s[18:19] op_sel_hi:[1,0]
	v_pk_mul_f32 v[38:39], v[184:185], s[18:19] op_sel_hi:[1,0]
	ds_read_b128 v[184:187], v182 offset:28224
	ds_read_b128 v[188:191], v182 offset:28288
	s_waitcnt lgkmcnt(1)
	v_mfma_f32_16x16x32_bf16 v[184:187], v[184:187], v[4:7], 0
	s_waitcnt lgkmcnt(0)
	v_mfma_f32_16x16x32_bf16 v[184:187], v[188:191], v[0:3], v[184:187]
	s_nop 7
	v_pk_mul_f32 v[44:45], v[186:187], s[18:19] op_sel_hi:[1,0]
	v_pk_mul_f32 v[48:49], v[184:185], s[18:19] op_sel_hi:[1,0]
	ds_read_b128 v[184:187], v182 offset:32256
	ds_read_b128 v[188:191], v182 offset:32320
	s_waitcnt lgkmcnt(1)
	v_mfma_f32_16x16x32_bf16 v[184:187], v[184:187], v[4:7], 0
	s_waitcnt lgkmcnt(0)
; __device__ __forceinline__ void phase_attn(const Args& a, unsigned char* smem, int tid, int lane, int wave, bf16_t* Yout) {
;     ...
;             float mx = -1e30f;
; #pragma unroll
;             for (int t = 0; t < 32; ++t) mx = fmaxf(fmaxf(fmaxf(st[t][0], st[t][1]), fmaxf(st[t][2], st[t][3])), mx);
;             mx = fmaxf(mx, __shfl_xor(mx, 16)); mx = fmaxf(mx, __shfl_xor(mx, 32));
;             float l = 0.f;
; #pragma unroll
;             for (int t = 0; t < 32; ++t) {
; #pragma unroll
;                 for (int e = 0; e < 4; ++e) { const float p = __expf(st[t][e] - mx); st[t][e] = p; l += p; } }
;             l += __shfl_xor(l, 16); l += __shfl_xor(l, 32);
	v_mfma_f32_16x16x32_bf16 v[184:187], v[188:191], v[0:3], v[184:187]
	s_nop 7
	v_pk_mul_f32 v[54:55], v[186:187], s[18:19] op_sel_hi:[1,0]
	v_pk_mul_f32 v[58:59], v[184:185], s[18:19] op_sel_hi:[1,0]
	ds_read_b128 v[184:187], v182 offset:32832
	ds_read_b128 v[188:191], v182 offset:32896
	s_waitcnt lgkmcnt(1)
	v_mfma_f32_16x16x32_bf16 v[4:7], v[184:187], v[4:7], 0
	s_waitcnt lgkmcnt(0)
	v_mfma_f32_16x16x32_bf16 v[2:5], v[188:191], v[0:3], v[4:7]
	s_nop 5
	v_max3_f32 v6, v71, v75, v68
	v_max3_f32 v7, v69, v70, v72
	v_pk_mul_f32 v[0:1], v[4:5], s[18:19] op_sel_hi:[1,0]
	v_pk_mul_f32 v[2:3], v[2:3], s[18:19] op_sel_hi:[1,0]
	v_max3_f32 v4, v73, v74, s47
	v_max3_f32 v5, v76, v77, v78
	v_max3_f32 v6, v6, v79, v80
	v_max3_f32 v7, v7, v81, v82
	v_max3_f32 v4, v4, v83, v84
	v_max3_f32 v5, v5, v85, v86
	v_max3_f32 v6, v6, v87, v88
	v_max3_f32 v7, v7, v89, v90
	v_max3_f32 v4, v4, v91, v92
	v_max3_f32 v5, v5, v93, v94
	v_max3_f32 v6, v6, v95, v96
	v_max3_f32 v7, v7, v97, v98
	v_max3_f32 v4, v4, v99, v100
	v_max3_f32 v5, v5, v101, v102
	v_max3_f32 v6, v6, v103, v104
	v_max3_f32 v7, v7, v105, v106
	v_max3_f32 v4, v4, v107, v108
	v_max3_f32 v5, v5, v109, v110
	v_max3_f32 v6, v6, v111, v147
	v_max3_f32 v7, v7, v148, v149
	v_max3_f32 v4, v4, v150, v151
	v_max3_f32 v5, v5, v152, v153
	v_max3_f32 v6, v6, v154, v155
	v_max3_f32 v7, v7, v216, v217
	v_max3_f32 v4, v4, v218, v219
	v_max3_f32 v5, v5, v220, v221
	v_max3_f32 v6, v6, v222, v223
	v_max3_f32 v7, v7, v224, v225
	v_max3_f32 v4, v4, v226, v66
	v_max3_f32 v5, v5, v67, v60
	v_max3_f32 v6, v6, v61, v64
	v_max3_f32 v7, v7, v65, v56
	v_max3_f32 v4, v4, v57, v62
	v_max3_f32 v5, v5, v63, v50
	v_max3_f32 v6, v6, v51, v52
	v_max3_f32 v7, v7, v53, v42
	v_max3_f32 v4, v4, v43, v46
	v_max3_f32 v5, v5, v47, v36
	v_max3_f32 v6, v6, v37, v40
	v_max3_f32 v7, v7, v41, v30
	v_max3_f32 v4, v4, v31, v34
	v_max3_f32 v5, v5, v35, v24
	v_max3_f32 v6, v6, v25, v28
	v_max3_f32 v7, v7, v29, v16
	v_max3_f32 v4, v4, v17, v22
	v_max3_f32 v5, v5, v23, v12
	v_max3_f32 v6, v6, v13, v14
	v_max3_f32 v7, v7, v15, v8
	v_max3_f32 v4, v4, v9, v20
	v_max3_f32 v5, v5, v21, v10
	v_max3_f32 v6, v6, v11, v32
	v_max3_f32 v7, v7, v33, v18
	v_max3_f32 v4, v4, v19, v38
	v_max3_f32 v5, v5, v39, v26
	v_max3_f32 v6, v6, v27, v48
	v_max3_f32 v7, v7, v49, v44
	v_max3_f32 v4, v4, v45, v58
	v_max3_f32 v5, v5, v59, v54
	v_max3_f32 v6, v6, v55, v0
	v_max3_f32 v7, v7, v1, v2
	v_max_f32_e32 v6, v6, v3
	v_max3_f32 v5, v5, v6, v7
	v_max_f32_e32 v5, v5, v4
	v_and_b32_e32 v6, 64, v183
	v_xor_b32_e32 v4, 16, v183
	v_add_u32_e32 v6, 64, v6
	v_cmp_lt_i32_e32 vcc, v4, v6
	s_nop 1
	v_cndmask_b32_e32 v4, v183, v4, vcc
	v_lshlrev_b32_e32 v4, 2, v4
	ds_bpermute_b32 v7, v4, v5
	s_waitcnt lgkmcnt(0)
	v_max_f32_e32 v7, v7, v7
	v_max_f32_e32 v7, v5, v7
	v_xor_b32_e32 v5, 32, v183
	v_cmp_lt_i32_e32 vcc, v5, v6
	s_nop 1
	v_cndmask_b32_e32 v5, v183, v5, vcc
	v_lshlrev_b32_e32 v5, 2, v5
	ds_bpermute_b32 v6, v5, v7
	s_waitcnt lgkmcnt(0)
	v_max_f32_e32 v6, v6, v6
	v_max_f32_e32 v6, v7, v6
	s_mov_b32 s24, 0x3fb8aa3b
	v_mul_f32_e32 v250, 0xbfb8aa3b, v6
	v_fma_f32 v68, v68, s24, v250
	v_exp_f32_e32 v185, v68
	v_fma_f32 v68, v71, s24, v250
	v_exp_f32_e32 v186, v68
	v_fma_f32 v68, v70, s24, v250
	v_exp_f32_e32 v187, v68
	v_fma_f32 v68, v73, s24, v250
	v_exp_f32_e32 v188, v68
	v_fma_f32 v68, v72, s24, v250
	v_exp_f32_e32 v189, v68
	v_fma_f32 v68, v75, s24, v250
	v_exp_f32_e32 v190, v68
	v_fma_f32 v68, v74, s24, v250
	v_exp_f32_e32 v191, v68
	v_fma_f32 v68, v77, s24, v250
	v_exp_f32_e32 v192, v68
	v_fma_f32 v68, v76, s24, v250
	v_exp_f32_e32 v193, v68
	v_fma_f32 v68, v79, s24, v250
	v_exp_f32_e32 v194, v68
	v_fma_f32 v68, v78, s24, v250
	v_exp_f32_e32 v195, v68
	v_fma_f32 v68, v81, s24, v250
	v_exp_f32_e32 v196, v68
	v_fma_f32 v68, v80, s24, v250
	v_exp_f32_e32 v197, v68
	v_fma_f32 v68, v83, s24, v250
	v_exp_f32_e32 v198, v68
	v_fma_f32 v68, v82, s24, v250
	v_fma_f32 v7, v69, s24, v250
	v_exp_f32_e32 v199, v68
	v_fma_f32 v68, v85, s24, v250
	v_exp_f32_e32 v184, v7
	v_exp_f32_e32 v200, v68
	v_fma_f32 v68, v84, s24, v250
	v_exp_f32_e32 v201, v68
	v_fma_f32 v68, v87, s24, v250
	v_add_f32_e32 v7, 0, v184
	v_add_f32_e32 v7, v185, v7
	v_exp_f32_e32 v202, v68
	v_fma_f32 v68, v86, s24, v250
	v_add_f32_e32 v7, v186, v7
	v_add_f32_e32 v7, v187, v7
	v_exp_f32_e32 v203, v68
	v_fma_f32 v68, v89, s24, v250
	v_add_f32_e32 v7, v188, v7
	v_add_f32_e32 v7, v189, v7
	v_exp_f32_e32 v204, v68
	v_fma_f32 v68, v88, s24, v250
	v_add_f32_e32 v7, v190, v7
	v_add_f32_e32 v7, v191, v7
	v_exp_f32_e32 v205, v68
	v_fma_f32 v68, v91, s24, v250
	v_add_f32_e32 v7, v192, v7
	v_add_f32_e32 v7, v193, v7
	v_exp_f32_e32 v206, v68
	v_fma_f32 v68, v90, s24, v250
	v_add_f32_e32 v7, v194, v7
	v_add_f32_e32 v7, v195, v7
	v_exp_f32_e32 v207, v68
	v_fma_f32 v68, v93, s24, v250
	v_add_f32_e32 v7, v196, v7
	v_add_f32_e32 v7, v197, v7
	v_exp_f32_e32 v208, v68
	v_fma_f32 v68, v92, s24, v250
	v_add_f32_e32 v7, v198, v7
	v_add_f32_e32 v7, v199, v7
	v_exp_f32_e32 v209, v68
	v_fma_f32 v68, v95, s24, v250
	v_add_f32_e32 v7, v200, v7
	v_add_f32_e32 v7, v201, v7
	v_exp_f32_e32 v210, v68
	v_fma_f32 v68, v94, s24, v250
	v_add_f32_e32 v7, v202, v7
	v_add_f32_e32 v7, v203, v7
	v_exp_f32_e32 v211, v68
	v_fma_f32 v68, v97, s24, v250
	v_add_f32_e32 v7, v204, v7
	v_add_f32_e32 v7, v205, v7
	v_exp_f32_e32 v212, v68
	v_fma_f32 v68, v96, s24, v250
	v_add_f32_e32 v7, v206, v7
	v_add_f32_e32 v7, v207, v7
	v_exp_f32_e32 v213, v68
	v_fma_f32 v68, v99, s24, v250
	v_add_f32_e32 v7, v208, v7
	v_add_f32_e32 v7, v209, v7
	v_exp_f32_e32 v214, v68
	v_fma_f32 v68, v98, s24, v250
	v_add_f32_e32 v7, v210, v7
	v_add_f32_e32 v7, v211, v7
	v_exp_f32_e32 v215, v68
; __device__ __forceinline__ void phase_attn(const Args& a, unsigned char* smem, int tid, int lane, int wave, bf16_t* Yout) {
;     ...
;             float l = 0.f;
; #pragma unroll
;             for (int t = 0; t < 32; ++t) {
; #pragma unroll
;                 for (int e = 0; e < 4; ++e) { const float p = __expf(st[t][e] - mx); st[t][e] = p; l += p; } }
;             l += __shfl_xor(l, 16); l += __shfl_xor(l, 32);
	v_add_f32_e32 v7, v212, v7
	v_add_f32_e32 v7, v213, v7
	v_add_f32_e32 v7, v214, v7
	v_add_f32_e32 v68, v215, v7
	v_fma_f32 v7, v101, s24, v250
	v_exp_f32_e32 v7, v7
	v_fma_f32 v93, v219, s24, v250
	v_fma_f32 v94, v222, s24, v250
	v_add_f32_e32 v69, v7, v68
	v_fma_f32 v68, v100, s24, v250
	v_exp_f32_e32 v68, v68
	v_exp_f32_e32 v93, v93
	v_fma_f32 v95, v221, s24, v250
	v_add_f32_e32 v70, v68, v69
	v_fma_f32 v69, v103, s24, v250
	v_exp_f32_e32 v69, v69
	v_exp_f32_e32 v94, v94
	v_fma_f32 v96, v224, s24, v250
	v_add_f32_e32 v71, v69, v70
	v_fma_f32 v70, v102, s24, v250
	v_exp_f32_e32 v70, v70
	v_exp_f32_e32 v95, v95
	v_fma_f32 v97, v223, s24, v250
	v_add_f32_e32 v72, v70, v71
	v_fma_f32 v71, v105, s24, v250
	v_exp_f32_e32 v71, v71
	v_exp_f32_e32 v96, v96
	v_fma_f32 v98, v226, s24, v250
	v_add_f32_e32 v73, v71, v72
	v_fma_f32 v72, v104, s24, v250
	v_exp_f32_e32 v72, v72
	v_exp_f32_e32 v97, v97
	v_fma_f32 v99, v225, s24, v250
	v_add_f32_e32 v74, v72, v73
	v_fma_f32 v73, v107, s24, v250
	v_exp_f32_e32 v73, v73
	v_exp_f32_e32 v98, v98
	v_fma_f32 v66, v66, s24, v250
	v_add_f32_e32 v75, v73, v74
	v_fma_f32 v74, v106, s24, v250
	v_exp_f32_e32 v74, v74
	v_exp_f32_e32 v99, v99
	v_fma_f32 v67, v67, s24, v250
	v_add_f32_e32 v76, v74, v75
	v_fma_f32 v75, v109, s24, v250
	v_exp_f32_e32 v75, v75
	v_exp_f32_e32 v66, v66
	v_fma_f32 v60, v60, s24, v250
	v_add_f32_e32 v77, v75, v76
	v_fma_f32 v76, v108, s24, v250
	v_exp_f32_e32 v76, v76
	v_exp_f32_e32 v67, v67
	v_fma_f32 v61, v61, s24, v250
	v_add_f32_e32 v78, v76, v77
	v_fma_f32 v77, v111, s24, v250
	v_exp_f32_e32 v77, v77
	v_exp_f32_e32 v60, v60
	v_fma_f32 v64, v64, s24, v250
	v_add_f32_e32 v79, v77, v78
	v_fma_f32 v78, v110, s24, v250
	v_exp_f32_e32 v78, v78
	v_exp_f32_e32 v61, v61
	v_fma_f32 v65, v65, s24, v250
	v_add_f32_e32 v80, v78, v79
	v_fma_f32 v79, v148, s24, v250
	v_exp_f32_e32 v79, v79
	v_exp_f32_e32 v64, v64
	v_fma_f32 v56, v56, s24, v250
	v_add_f32_e32 v81, v79, v80
	v_fma_f32 v80, v147, s24, v250
	v_exp_f32_e32 v80, v80
	v_exp_f32_e32 v65, v65
	v_fma_f32 v57, v57, s24, v250
	v_add_f32_e32 v82, v80, v81
	v_fma_f32 v81, v150, s24, v250
	v_exp_f32_e32 v81, v81
	v_exp_f32_e32 v56, v56
	v_fma_f32 v62, v62, s24, v250
	v_add_f32_e32 v83, v81, v82
	v_fma_f32 v82, v149, s24, v250
	v_exp_f32_e32 v82, v82
	v_exp_f32_e32 v57, v57
	v_fma_f32 v63, v63, s24, v250
	v_add_f32_e32 v84, v82, v83
	v_fma_f32 v83, v152, s24, v250
	v_exp_f32_e32 v83, v83
	v_exp_f32_e32 v62, v62
	v_fma_f32 v50, v50, s24, v250
	v_add_f32_e32 v85, v83, v84
	v_fma_f32 v84, v151, s24, v250
	v_exp_f32_e32 v84, v84
	v_exp_f32_e32 v63, v63
	v_fma_f32 v51, v51, s24, v250
	v_add_f32_e32 v86, v84, v85
	v_fma_f32 v85, v154, s24, v250
	v_exp_f32_e32 v85, v85
	v_exp_f32_e32 v50, v50
	v_fma_f32 v52, v52, s24, v250
	v_add_f32_e32 v87, v85, v86
	v_fma_f32 v86, v153, s24, v250
	v_exp_f32_e32 v86, v86
	v_exp_f32_e32 v51, v51
	v_fma_f32 v53, v53, s24, v250
	v_add_f32_e32 v88, v86, v87
	v_fma_f32 v87, v216, s24, v250
	v_exp_f32_e32 v87, v87
	v_exp_f32_e32 v52, v52
	v_fma_f32 v42, v42, s24, v250
	v_add_f32_e32 v89, v87, v88
	v_fma_f32 v88, v155, s24, v250
	v_exp_f32_e32 v88, v88
	v_exp_f32_e32 v53, v53
	v_fma_f32 v43, v43, s24, v250
	v_add_f32_e32 v90, v88, v89
	v_fma_f32 v89, v218, s24, v250
	v_exp_f32_e32 v89, v89
	v_exp_f32_e32 v42, v42
	v_fma_f32 v46, v46, s24, v250
	v_add_f32_e32 v91, v89, v90
	v_fma_f32 v90, v217, s24, v250
	v_exp_f32_e32 v90, v90
	v_exp_f32_e32 v43, v43
	v_fma_f32 v47, v47, s24, v250
	v_add_f32_e32 v92, v90, v91
	v_fma_f32 v91, v220, s24, v250
	v_exp_f32_e32 v91, v91
	v_exp_f32_e32 v46, v46
	v_fma_f32 v36, v36, s24, v250
	v_add_f32_e32 v92, v91, v92
	v_add_f32_e32 v92, v93, v92
	v_add_f32_e32 v92, v94, v92
	v_add_f32_e32 v92, v95, v92
	v_add_f32_e32 v92, v96, v92
	v_add_f32_e32 v92, v97, v92
	v_add_f32_e32 v92, v98, v92
	v_add_f32_e32 v92, v99, v92
	v_add_f32_e32 v92, v66, v92
	v_add_f32_e32 v92, v67, v92
	v_add_f32_e32 v92, v60, v92
	v_add_f32_e32 v92, v61, v92
	v_add_f32_e32 v92, v64, v92
	v_add_f32_e32 v92, v65, v92
	v_add_f32_e32 v92, v56, v92
	v_add_f32_e32 v92, v57, v92
	v_add_f32_e32 v92, v62, v92
	v_add_f32_e32 v92, v63, v92
	v_add_f32_e32 v92, v50, v92
	v_add_f32_e32 v92, v51, v92
	v_add_f32_e32 v92, v52, v92
	v_add_f32_e32 v92, v53, v92
	v_exp_f32_e32 v47, v47
	v_fma_f32 v37, v37, s24, v250
	v_fma_f32 v9, v9, s24, v250
	v_add_f32_e32 v92, v42, v92
	v_exp_f32_e32 v100, v36
	v_fma_f32 v40, v40, s24, v250
	v_add_f32_e32 v92, v43, v92
	v_exp_f32_e32 v37, v37
	v_fma_f32 v41, v41, s24, v250
	v_exp_f32_e32 v105, v9
	v_fma_f32 v9, v20, s24, v250
	v_add_f32_e32 v92, v46, v92
	v_exp_f32_e32 v40, v40
	v_fma_f32 v30, v30, s24, v250
	v_add_f32_e32 v92, v47, v92
	v_exp_f32_e32 v41, v41
	v_fma_f32 v31, v31, s24, v250
	v_exp_f32_e32 v20, v9
	v_fma_f32 v9, v21, s24, v250
	v_add_f32_e32 v36, v100, v92
	v_exp_f32_e32 v30, v30
	v_fma_f32 v34, v34, s24, v250
	v_add_f32_e32 v36, v37, v36
	v_exp_f32_e32 v31, v31
	v_fma_f32 v35, v35, s24, v250
	v_exp_f32_e32 v21, v9
	v_fma_f32 v9, v10, s24, v250
	v_add_f32_e32 v36, v40, v36
	v_exp_f32_e32 v34, v34
	v_fma_f32 v24, v24, s24, v250
	v_add_f32_e32 v36, v41, v36
	v_exp_f32_e32 v35, v35
	v_fma_f32 v25, v25, s24, v250
	v_exp_f32_e32 v106, v9
	v_fma_f32 v9, v11, s24, v250
	v_add_f32_e32 v36, v30, v36
	v_exp_f32_e32 v24, v24
	v_fma_f32 v28, v28, s24, v250
	v_add_f32_e32 v36, v31, v36
	v_exp_f32_e32 v25, v25
	v_fma_f32 v29, v29, s24, v250
	v_exp_f32_e32 v107, v9
	v_fma_f32 v9, v32, s24, v250
	v_add_f32_e32 v36, v34, v36
	v_exp_f32_e32 v28, v28
	v_fma_f32 v16, v16, s24, v250
	v_add_f32_e32 v36, v35, v36
	v_exp_f32_e32 v29, v29
	v_fma_f32 v17, v17, s24, v250
	v_exp_f32_e32 v147, v9
	v_fma_f32 v9, v33, s24, v250
; __device__ __forceinline__ unsigned pk2(float lo, float hi) { const f32x2 v = {lo, hi}; const bf16x2_t b = __builtin_convertvector(v, bf16x2_t); return __builtin_bit_cast(unsigned, b); }
; #define ATT_VLOAD16(bt, dstb) do { _Pragma("unroll") for (int pp_ = 0; pp_ < 4; ++pp_) { \
;                 const size_t tokb_ = (size_t)b * 16384 + (rs + (bt) * 4 + pp_) * 64 + kc0 + 8 * g; \
;                 _Pragma("unroll") for (int mt_ = 0; mt_ < 4; ++mt_) vb2[dstb][pp_ * 4 + mt_] = *(const bf16x8*)(AVT + (size_t)(h * 64 + mt_ * 16 + q16) * MR + tokb_); } } while (0)
; __device__ __forceinline__ void phase_attn(const Args& a, unsigned char* smem, int tid, int lane, int wave, bf16_t* Yout) {
;     ...
;             float l = 0.f;
; #pragma unroll
;             for (int t = 0; t < 32; ++t) {
; #pragma unroll
;                 for (int e = 0; e < 4; ++e) { const float p = __expf(st[t][e] - mx); st[t][e] = p; l += p; } }
;             l += __shfl_xor(l, 16); l += __shfl_xor(l, 32);
;             bf16x8 pb[16];
; #pragma unroll
;             for (int p = 0; p < 16; ++p) { u32x4 pw; pw.x = pk2(st[2 * p][0], st[2 * p][1]); pw.y = pk2(st[2 * p][2], st[2 * p][3]); pw.z = pk2(st[2 * p + 1][0], st[2 * p + 1][1]); pw.w = pk2(st[2 * p + 1][2], st[2 * p + 1][3]);
;                 pb[p] = __builtin_bit_cast(bf16x8, pw); }
;             f32x4 o[4];
; #pragma unroll
;             for (int mt = 0; mt < 4; ++mt) o[mt] = (f32x4){0.f, 0.f, 0.f, 0.f};
;             bf16x8 vb2[1][16];
;     ...
;             ATT_VLOAD16(0, 0);
	v_add_f32_e32 v36, v24, v36
	v_exp_f32_e32 v16, v16
	v_fma_f32 v22, v22, s24, v250
	v_add_f32_e32 v36, v25, v36
	v_exp_f32_e32 v17, v17
	v_fma_f32 v23, v23, s24, v250
	v_fma_f32 v13, v13, s24, v250
	v_exp_f32_e32 v148, v9
	v_fma_f32 v9, v18, s24, v250
	v_add_f32_e32 v36, v28, v36
	v_exp_f32_e32 v22, v22
	v_fma_f32 v12, v12, s24, v250
	v_add_f32_e32 v36, v29, v36
	v_exp_f32_e32 v23, v23
	v_exp_f32_e32 v101, v13
	v_fma_f32 v13, v14, s24, v250
	v_exp_f32_e32 v18, v9
	v_fma_f32 v9, v19, s24, v250
	v_add_f32_e32 v36, v16, v36
	v_exp_f32_e32 v92, v12
	v_add_f32_e32 v36, v17, v36
	v_exp_f32_e32 v102, v13
	v_fma_f32 v13, v15, s24, v250
	v_exp_f32_e32 v19, v9
	v_fma_f32 v9, v38, s24, v250
	v_add_f32_e32 v36, v22, v36
	v_fma_f32 v8, v8, s24, v250
	v_add_f32_e32 v36, v23, v36
	v_exp_f32_e32 v103, v13
	v_exp_f32_e32 v149, v9
	v_fma_f32 v9, v39, s24, v250
	v_add_f32_e32 v12, v92, v36
	v_exp_f32_e32 v104, v8
	v_add_f32_e32 v12, v101, v12
	v_exp_f32_e32 v150, v9
	v_fma_f32 v9, v26, s24, v250
	v_add_f32_e32 v12, v102, v12
	v_add_f32_e32 v12, v103, v12
	v_exp_f32_e32 v151, v9
	v_fma_f32 v9, v27, s24, v250
	v_add_f32_e32 v8, v104, v12
	v_add_f32_e32 v8, v105, v8
	v_exp_f32_e32 v152, v9
	v_fma_f32 v9, v48, s24, v250
	v_add_f32_e32 v8, v20, v8
	v_add_f32_e32 v8, v21, v8
	v_exp_f32_e32 v153, v9
	v_fma_f32 v9, v49, s24, v250
	v_add_f32_e32 v8, v106, v8
	v_add_f32_e32 v8, v107, v8
	v_exp_f32_e32 v154, v9
	v_fma_f32 v9, v44, s24, v250
	v_add_f32_e32 v8, v147, v8
	v_add_f32_e32 v8, v148, v8
	v_exp_f32_e32 v44, v9
	v_fma_f32 v9, v45, s24, v250
	v_add_f32_e32 v8, v18, v8
	v_add_f32_e32 v8, v19, v8
	v_exp_f32_e32 v45, v9
	v_fma_f32 v9, v58, s24, v250
	v_add_f32_e32 v8, v149, v8
	v_add_f32_e32 v8, v150, v8
	v_exp_f32_e32 v58, v9
	v_fma_f32 v9, v59, s24, v250
	v_add_f32_e32 v8, v151, v8
	v_add_f32_e32 v8, v152, v8
	v_exp_f32_e32 v59, v9
	v_fma_f32 v9, v54, s24, v250
	v_add_f32_e32 v8, v153, v8
	v_add_f32_e32 v8, v154, v8
	v_exp_f32_e32 v54, v9
	v_fma_f32 v9, v55, s24, v250
	v_add_f32_e32 v8, v44, v8
	v_fma_f32 v2, v2, s24, v250
	v_add_f32_e32 v8, v45, v8
	v_exp_f32_e32 v55, v9
	v_fma_f32 v3, v3, s24, v250
	v_add_f32_e32 v8, v58, v8
	v_exp_f32_e32 v155, v2
	v_fma_f32 v0, v0, s24, v250
	v_add_f32_e32 v8, v59, v8
	v_exp_f32_e32 v218, v3
	v_fma_f32 v1, v1, s24, v250
	v_add_f32_e32 v8, v54, v8
	v_exp_f32_e32 v219, v0
	v_add_f32_e32 v8, v55, v8
	v_exp_f32_e32 v220, v1
	v_add_f32_e32 v2, v155, v8
	v_add_f32_e32 v2, v218, v2
	v_cvt_pk_bf16_f32 v38, v40, v41
	v_lshl_add_u64 v[40:41], v[132:133], 0, v[114:115]
	v_add_f32_e32 v0, v219, v2
	v_cvt_pk_bf16_f32 v26, v147, v148
	v_lshl_add_u64 v[40:41], v[40:41], 0, s[12:13]
	v_mov_b32_e32 v147, v115
	v_add_f32_e32 v0, v220, v0
	v_cvt_pk_bf16_f32 v32, v34, v35
	v_cvt_pk_bf16_f32 v34, v28, v29
	v_cvt_pk_bf16_f32 v28, v22, v23
	v_cvt_pk_bf16_f32 v27, v18, v19
	v_cvt_pk_bf16_f32 v22, v153, v154
	v_cvt_pk_bf16_f32 v18, v155, v218
	v_lshl_add_u64 v[154:155], v[40:41], 0, v[146:147]
	ds_bpermute_b32 v1, v4, v0
	v_cvt_pk_bf16_f32 v33, v24, v25
	v_cvt_pk_bf16_f32 v24, v20, v21
	v_cvt_pk_bf16_f32 v21, v151, v152
	v_add_co_u32_e32 v152, vcc, s48, v154
	v_cvt_pk_bf16_f32 v20, v149, v150
	s_nop 0
	v_addc_co_u32_e32 v153, vcc, 0, v155, vcc
	v_add_co_u32_e32 v150, vcc, s49, v154
	s_waitcnt lgkmcnt(0)
	v_add_f32_e32 v216, v0, v1
	v_addc_co_u32_e32 v151, vcc, 0, v155, vcc
	v_add_co_u32_e32 v148, vcc, s50, v154
	ds_bpermute_b32 v217, v5, v216
	s_nop 0
	v_addc_co_u32_e32 v149, vcc, 0, v155, vcc
	v_cvt_pk_bf16_f32 v12, v7, v68
	v_cvt_pk_bf16_f32 v13, v69, v70
	v_cvt_pk_bf16_f32 v14, v71, v72
	v_cvt_pk_bf16_f32 v15, v73, v74
	v_cvt_pk_bf16_f32 v8, v75, v76
	v_cvt_pk_bf16_f32 v9, v77, v78
	v_cvt_pk_bf16_f32 v10, v79, v80
	v_cvt_pk_bf16_f32 v11, v81, v82
	v_cvt_pk_bf16_f32 v4, v83, v84
	v_cvt_pk_bf16_f32 v5, v85, v86
	v_cvt_pk_bf16_f32 v6, v87, v88
	v_cvt_pk_bf16_f32 v7, v89, v90
	v_cvt_pk_bf16_f32 v0, v91, v93
	v_cvt_pk_bf16_f32 v1, v94, v95
	v_cvt_pk_bf16_f32 v2, v96, v97
	v_cvt_pk_bf16_f32 v3, v98, v99
	v_cvt_pk_bf16_f32 v108, v66, v67
	v_cvt_pk_bf16_f32 v109, v60, v61
	v_cvt_pk_bf16_f32 v110, v64, v65
	v_cvt_pk_bf16_f32 v111, v56, v57
	v_cvt_pk_bf16_f32 v48, v62, v63
	v_cvt_pk_bf16_f32 v49, v50, v51
	v_cvt_pk_bf16_f32 v50, v52, v53
	v_cvt_pk_bf16_f32 v51, v42, v43
	v_cvt_pk_bf16_f32 v36, v46, v47
	v_cvt_pk_bf16_f32 v37, v100, v37
	v_cvt_pk_bf16_f32 v39, v30, v31
	v_cvt_pk_bf16_f32 v35, v16, v17
	v_cvt_pk_bf16_f32 v29, v92, v101
	v_cvt_pk_bf16_f32 v30, v102, v103
	v_cvt_pk_bf16_f32 v31, v104, v105
	v_cvt_pk_bf16_f32 v25, v106, v107
	v_cvt_pk_bf16_f32 v23, v44, v45
	v_cvt_pk_bf16_f32 v16, v58, v59
	v_cvt_pk_bf16_f32 v17, v54, v55
	global_load_dwordx4 v[40:43], v[154:155], off
	global_load_dwordx4 v[44:47], v[152:153], off
	global_load_dwordx4 v[52:55], v[150:151], off
	global_load_dwordx4 v[56:59], v[148:149], off
	global_load_dwordx4 v[60:63], v[154:155], off offset:128
	global_load_dwordx4 v[64:67], v[152:153], off offset:128
	global_load_dwordx4 v[68:71], v[150:151], off offset:128
	global_load_dwordx4 v[72:75], v[148:149], off offset:128
	global_load_dwordx4 v[76:79], v[154:155], off offset:256
	global_load_dwordx4 v[80:83], v[152:153], off offset:256
	global_load_dwordx4 v[84:87], v[150:151], off offset:256
	global_load_dwordx4 v[88:91], v[148:149], off offset:256
	global_load_dwordx4 v[92:95], v[154:155], off offset:384
	global_load_dwordx4 v[96:99], v[152:153], off offset:384
	global_load_dwordx4 v[100:103], v[150:151], off offset:384
	global_load_dwordx4 v[104:107], v[148:149], off offset:384
	v_cvt_pk_bf16_f32 v19, v219, v220
	ds_read_b128 v[218:221], v169 offset:36864
	ds_read_b128 v[222:225], v169 offset:45312
	ds_read_b128 v[226:229], v169 offset:53760
	ds_read_b128 v[230:233], v170 offset:36864
	s_waitcnt lgkmcnt(3)
; __device__ __forceinline__ f32x4 mfma16(bf16x8 a, bf16x8 b, f32x4 c) { return __builtin_amdgcn_mfma_f32_16x16x32_bf16(a, b, c, 0, 0, 0); }
; #define ATT_VLOAD16(bt, dstb) do { _Pragma("unroll") for (int pp_ = 0; pp_ < 4; ++pp_) { \
;                 const size_t tokb_ = (size_t)b * 16384 + (rs + (bt) * 4 + pp_) * 64 + kc0 + 8 * g; \
;                 _Pragma("unroll") for (int mt_ = 0; mt_ < 4; ++mt_) vb2[dstb][pp_ * 4 + mt_] = *(const bf16x8*)(AVT + (size_t)(h * 64 + mt_ * 16 + q16) * MR + tokb_); } } while (0)
; __device__ __forceinline__ void phase_attn(const Args& a, unsigned char* smem, int tid, int lane, int wave, bf16_t* Yout) {
;     ...
;             ATT_VLOAD16(0, 0);
;             asm volatile("" ::: "memory");
; #pragma unroll
;             for (int p = 8; p < 16; ++p) {
; #pragma unroll
;                 for (int mt = 0; mt < 4; ++mt) o[mt] = mfma16(*(const bf16x8*)(Vs + (mt * 16 + q16) * 264 + (p - 8) * 32 + 8 * g), pb[p], o[mt]);
;             }
;             asm volatile("" ::: "memory");
; #pragma unroll
;             for (int bt = 0; bt < 2; ++bt) {
;                 if (bt == 1) { ATT_VLOAD16(1, 0); asm volatile("" ::: "memory"); }
; #pragma unroll
;                 for (int pp = 0; pp < 4; ++pp)
; #pragma unroll
;                     for (int mt = 0; mt < 4; ++mt) o[mt] = mfma16(vb2[0][pp * 4 + mt], pb[bt * 4 + pp], o[mt]);
	v_mfma_f32_16x16x32_bf16 v[218:221], v[218:221], v[108:111], 0
	s_waitcnt lgkmcnt(2)
	v_mfma_f32_16x16x32_bf16 v[222:225], v[222:225], v[108:111], 0
	s_waitcnt lgkmcnt(1)
	v_mfma_f32_16x16x32_bf16 v[226:229], v[226:229], v[108:111], 0
	s_waitcnt lgkmcnt(0)
	v_mfma_f32_16x16x32_bf16 v[108:111], v[230:233], v[108:111], 0
	ds_read_b128 v[230:233], v169 offset:36928
	s_waitcnt lgkmcnt(0)
	v_mfma_f32_16x16x32_bf16 v[218:221], v[230:233], v[48:51], v[218:221]
	ds_read_b128 v[230:233], v169 offset:45376
	s_waitcnt lgkmcnt(0)
	v_mfma_f32_16x16x32_bf16 v[222:225], v[230:233], v[48:51], v[222:225]
	ds_read_b128 v[230:233], v169 offset:53824
	s_waitcnt lgkmcnt(0)
	v_mfma_f32_16x16x32_bf16 v[226:229], v[230:233], v[48:51], v[226:229]
	ds_read_b128 v[230:233], v170 offset:36928
	s_waitcnt lgkmcnt(0)
	v_mfma_f32_16x16x32_bf16 v[48:51], v[230:233], v[48:51], v[108:111]
	s_nop 2
	ds_read_b128 v[108:111], v169 offset:36992
	s_waitcnt lgkmcnt(0)
	v_mfma_f32_16x16x32_bf16 v[108:111], v[108:111], v[36:39], v[218:221]
	s_nop 2
	ds_read_b128 v[218:221], v169 offset:45440
	s_waitcnt lgkmcnt(0)
	v_mfma_f32_16x16x32_bf16 v[218:221], v[218:221], v[36:39], v[222:225]
	s_nop 2
	ds_read_b128 v[222:225], v169 offset:53888
	s_waitcnt lgkmcnt(0)
	v_mfma_f32_16x16x32_bf16 v[222:225], v[222:225], v[36:39], v[226:229]
	s_nop 2
	ds_read_b128 v[226:229], v170 offset:36992
	s_waitcnt lgkmcnt(0)
	v_mfma_f32_16x16x32_bf16 v[36:39], v[226:229], v[36:39], v[48:51]
	s_nop 2
	ds_read_b128 v[48:51], v169 offset:37056
	s_waitcnt lgkmcnt(0)
	v_mfma_f32_16x16x32_bf16 v[48:51], v[48:51], v[32:35], v[108:111]
	s_nop 2
	ds_read_b128 v[108:111], v169 offset:45504
	s_waitcnt lgkmcnt(0)
	v_mfma_f32_16x16x32_bf16 v[108:111], v[108:111], v[32:35], v[218:221]
	s_nop 2
	ds_read_b128 v[218:221], v169 offset:53952
	s_waitcnt lgkmcnt(0)
	v_mfma_f32_16x16x32_bf16 v[218:221], v[218:221], v[32:35], v[222:225]
	s_nop 2
	ds_read_b128 v[222:225], v170 offset:37056
	s_waitcnt lgkmcnt(0)
	v_mfma_f32_16x16x32_bf16 v[32:35], v[222:225], v[32:35], v[36:39]
	s_nop 2
	ds_read_b128 v[36:39], v169 offset:37120
	s_waitcnt lgkmcnt(0)
	v_mfma_f32_16x16x32_bf16 v[36:39], v[36:39], v[28:31], v[48:51]
	s_nop 2
	ds_read_b128 v[48:51], v169 offset:45568
	s_waitcnt lgkmcnt(0)
	v_mfma_f32_16x16x32_bf16 v[48:51], v[48:51], v[28:31], v[108:111]
	s_nop 2
	ds_read_b128 v[108:111], v169 offset:54016
	s_waitcnt lgkmcnt(0)
	v_mfma_f32_16x16x32_bf16 v[108:111], v[108:111], v[28:31], v[218:221]
	s_nop 2
	ds_read_b128 v[218:221], v170 offset:37120
	s_waitcnt lgkmcnt(0)
	v_mfma_f32_16x16x32_bf16 v[28:31], v[218:221], v[28:31], v[32:35]
	s_nop 2
	ds_read_b128 v[32:35], v169 offset:37184
	s_waitcnt lgkmcnt(0)
	v_mfma_f32_16x16x32_bf16 v[32:35], v[32:35], v[24:27], v[36:39]
	s_nop 2
	ds_read_b128 v[36:39], v169 offset:45632
	s_waitcnt lgkmcnt(0)
	v_mfma_f32_16x16x32_bf16 v[36:39], v[36:39], v[24:27], v[48:51]
	s_nop 2
	ds_read_b128 v[48:51], v169 offset:54080
	s_waitcnt lgkmcnt(0)
	v_mfma_f32_16x16x32_bf16 v[48:51], v[48:51], v[24:27], v[108:111]
	s_nop 2
	ds_read_b128 v[108:111], v170 offset:37184
	s_waitcnt lgkmcnt(0)
	v_mfma_f32_16x16x32_bf16 v[24:27], v[108:111], v[24:27], v[28:31]
	s_nop 2
	ds_read_b128 v[28:31], v169 offset:37248
	v_cvt_pk_bf16_f32 v108, v184, v185
	v_cvt_pk_bf16_f32 v109, v186, v187
	s_waitcnt lgkmcnt(0)
	v_mfma_f32_16x16x32_bf16 v[28:31], v[28:31], v[20:23], v[32:35]
	s_nop 2
	ds_read_b128 v[32:35], v169 offset:45696
	v_cvt_pk_bf16_f32 v110, v188, v189
	v_cvt_pk_bf16_f32 v111, v190, v191
	s_waitcnt lgkmcnt(0)
	v_mfma_f32_16x16x32_bf16 v[32:35], v[32:35], v[20:23], v[36:39]
	s_nop 2
	ds_read_b128 v[36:39], v169 offset:54144
	s_waitcnt lgkmcnt(0)
	v_mfma_f32_16x16x32_bf16 v[36:39], v[36:39], v[20:23], v[48:51]
	s_nop 2
	ds_read_b128 v[48:51], v170 offset:37248
	s_waitcnt lgkmcnt(0)
	v_mfma_f32_16x16x32_bf16 v[20:23], v[48:51], v[20:23], v[24:27]
	s_nop 2
	ds_read_b128 v[24:27], v169 offset:37312
	v_cvt_pk_bf16_f32 v48, v192, v193
	v_cvt_pk_bf16_f32 v49, v194, v195
	s_waitcnt lgkmcnt(0)
	v_mfma_f32_16x16x32_bf16 v[24:27], v[24:27], v[16:19], v[28:31]
	s_nop 2
	ds_read_b128 v[28:31], v169 offset:45760
	v_cvt_pk_bf16_f32 v50, v196, v197
	v_cvt_pk_bf16_f32 v51, v198, v199
	s_waitcnt lgkmcnt(0)
	v_mfma_f32_16x16x32_bf16 v[28:31], v[28:31], v[16:19], v[32:35]
	s_nop 2
	ds_read_b128 v[32:35], v169 offset:54208
	s_waitcnt lgkmcnt(0)
	v_mfma_f32_16x16x32_bf16 v[32:35], v[32:35], v[16:19], v[36:39]
	s_nop 2
	ds_read_b128 v[36:39], v170 offset:37312
	s_waitcnt lgkmcnt(0)
	v_mfma_f32_16x16x32_bf16 v[16:19], v[36:39], v[16:19], v[20:23]
	s_nop 2
	v_cvt_pk_bf16_f32 v20, v200, v201
	v_cvt_pk_bf16_f32 v21, v202, v203
	v_cvt_pk_bf16_f32 v22, v204, v205
	s_waitcnt vmcnt(15)
	v_mfma_f32_16x16x32_bf16 v[24:27], v[40:43], v[108:111], v[24:27]
	v_cvt_pk_bf16_f32 v23, v206, v207
	v_cvt_pk_bf16_f32 v36, v208, v209
	v_cvt_pk_bf16_f32 v37, v210, v211
	s_waitcnt vmcnt(14)
	v_mfma_f32_16x16x32_bf16 v[28:31], v[44:47], v[108:111], v[28:31]
	v_cvt_pk_bf16_f32 v38, v212, v213
	v_cvt_pk_bf16_f32 v39, v214, v215
	s_waitcnt vmcnt(13)
	v_mfma_f32_16x16x32_bf16 v[32:35], v[52:55], v[108:111], v[32:35]
	s_waitcnt vmcnt(12)
	v_mfma_f32_16x16x32_bf16 v[16:19], v[56:59], v[108:111], v[16:19]
	s_waitcnt vmcnt(11)
	v_mfma_f32_16x16x32_bf16 v[24:27], v[60:63], v[48:51], v[24:27]
	s_waitcnt vmcnt(10)
	v_mfma_f32_16x16x32_bf16 v[28:31], v[64:67], v[48:51], v[28:31]
	s_waitcnt vmcnt(9)
	v_mfma_f32_16x16x32_bf16 v[32:35], v[68:71], v[48:51], v[32:35]
	s_waitcnt vmcnt(8)
	v_mfma_f32_16x16x32_bf16 v[16:19], v[72:75], v[48:51], v[16:19]
	s_waitcnt vmcnt(7)
	v_mfma_f32_16x16x32_bf16 v[24:27], v[76:79], v[20:23], v[24:27]
	s_waitcnt vmcnt(6)
; __device__ __forceinline__ unsigned pk2(float lo, float hi) { const f32x2 v = {lo, hi}; const bf16x2_t b = __builtin_convertvector(v, bf16x2_t); return __builtin_bit_cast(unsigned, b); }
; __device__ __forceinline__ float silu_f(float v) { return v * __builtin_amdgcn_rcpf(1.f + __expf(-v)); }
; __device__ __forceinline__ f32x4 mfma16(bf16x8 a, bf16x8 b, f32x4 c) { return __builtin_amdgcn_mfma_f32_16x16x32_bf16(a, b, c, 0, 0, 0); }
; #define ATT_VLOAD16(bt, dstb) do { _Pragma("unroll") for (int pp_ = 0; pp_ < 4; ++pp_) { \
;                 const size_t tokb_ = (size_t)b * 16384 + (rs + (bt) * 4 + pp_) * 64 + kc0 + 8 * g; \
;                 _Pragma("unroll") for (int mt_ = 0; mt_ < 4; ++mt_) vb2[dstb][pp_ * 4 + mt_] = *(const bf16x8*)(AVT + (size_t)(h * 64 + mt_ * 16 + q16) * MR + tokb_); } } while (0)
; __device__ __forceinline__ void phase_attn(const Args& a, unsigned char* smem, int tid, int lane, int wave, bf16_t* Yout) {
;     ...
;             for (int bt = 0; bt < 2; ++bt) {
;                 if (bt == 1) { ATT_VLOAD16(1, 0); asm volatile("" ::: "memory"); }
; #pragma unroll
;                 for (int pp = 0; pp < 4; ++pp)
; #pragma unroll
;                     for (int mt = 0; mt < 4; ++mt) o[mt] = mfma16(vb2[0][pp * 4 + mt], pb[bt * 4 + pp], o[mt]);
;             }
;     ...
;             const float inv = 1.f / l;
; #pragma unroll
;             for (int mt = 0; mt < 4; ++mt) {
;                 const size_t off = qrow * 1024 + h * 64 + mt * 16 + 4 * g;
;                 const u32x2 z = *(const u32x2*)(AZ + off);
;                 u32x2 w; w.x = pk2(o[mt][0] * inv * silu_f(bflo(z.x)), o[mt][1] * inv * silu_f(bfhi(z.x)));
;                 w.y = pk2(o[mt][2] * inv * silu_f(bflo(z.y)), o[mt][3] * inv * silu_f(bfhi(z.y)));
;                 *(u32x2*)(Yout + off) = w;
;             }
	v_mfma_f32_16x16x32_bf16 v[40:43], v[80:83], v[20:23], v[28:31]
	s_waitcnt vmcnt(5)
	v_mfma_f32_16x16x32_bf16 v[32:35], v[84:87], v[20:23], v[32:35]
	s_waitcnt vmcnt(4)
	v_mfma_f32_16x16x32_bf16 v[16:19], v[88:91], v[20:23], v[16:19]
	s_waitcnt vmcnt(3)
	v_mfma_f32_16x16x32_bf16 v[28:31], v[92:95], v[36:39], v[24:27]
	s_waitcnt vmcnt(2)
	v_mfma_f32_16x16x32_bf16 v[24:27], v[96:99], v[36:39], v[40:43]
	s_waitcnt vmcnt(1)
	v_mfma_f32_16x16x32_bf16 v[20:23], v[100:103], v[36:39], v[32:35]
	s_waitcnt vmcnt(0)
	v_mfma_f32_16x16x32_bf16 v[16:19], v[104:107], v[36:39], v[16:19]
	s_nop 0
	global_load_dwordx4 v[32:35], v[154:155], off offset:512
	global_load_dwordx4 v[36:39], v[152:153], off offset:512
	global_load_dwordx4 v[40:43], v[150:151], off offset:512
	global_load_dwordx4 v[44:47], v[148:149], off offset:512
	global_load_dwordx4 v[48:51], v[154:155], off offset:640
	global_load_dwordx4 v[52:55], v[152:153], off offset:640
	global_load_dwordx4 v[56:59], v[150:151], off offset:640
	global_load_dwordx4 v[60:63], v[148:149], off offset:640
	global_load_dwordx4 v[64:67], v[154:155], off offset:768
	global_load_dwordx4 v[68:71], v[152:153], off offset:768
	global_load_dwordx4 v[72:75], v[150:151], off offset:768
	global_load_dwordx4 v[76:79], v[148:149], off offset:768
	global_load_dwordx4 v[80:83], v[154:155], off offset:896
	global_load_dwordx4 v[84:87], v[152:153], off offset:896
	global_load_dwordx4 v[88:91], v[150:151], off offset:896
	global_load_dwordx4 v[92:95], v[148:149], off offset:896
	s_mov_b32 vcc_lo, s51
	s_mov_b32 vcc_hi, 0
	v_lshl_add_u64 v[248:249], v[136:137], 0, vcc
	v_lshl_add_u64 v[240:241], v[248:249], 0, v[144:145]
	v_lshl_add_u64 v[242:243], v[248:249], 0, v[142:143]
	v_lshl_add_u64 v[244:245], v[248:249], 0, v[140:141]
	v_lshl_add_u64 v[246:247], v[248:249], 0, v[138:139]
	global_load_dwordx2 v[232:233], v[240:241], off
	global_load_dwordx2 v[234:235], v[242:243], off
	global_load_dwordx2 v[236:237], v[244:245], off
	global_load_dwordx2 v[238:239], v[246:247], off
	s_waitcnt vmcnt(19)
	v_mfma_f32_16x16x32_bf16 v[28:31], v[32:35], v[12:15], v[28:31]
	s_waitcnt vmcnt(18)
	v_mfma_f32_16x16x32_bf16 v[24:27], v[36:39], v[12:15], v[24:27]
	s_waitcnt vmcnt(17)
	v_mfma_f32_16x16x32_bf16 v[20:23], v[40:43], v[12:15], v[20:23]
	s_waitcnt vmcnt(16)
	v_mfma_f32_16x16x32_bf16 v[12:15], v[44:47], v[12:15], v[16:19]
	s_waitcnt vmcnt(15)
	v_mfma_f32_16x16x32_bf16 v[16:19], v[48:51], v[8:11], v[28:31]
	s_waitcnt vmcnt(14)
	v_mfma_f32_16x16x32_bf16 v[24:27], v[52:55], v[8:11], v[24:27]
	s_waitcnt vmcnt(13)
	v_mfma_f32_16x16x32_bf16 v[20:23], v[56:59], v[8:11], v[20:23]
	s_waitcnt vmcnt(12)
	v_mfma_f32_16x16x32_bf16 v[8:11], v[60:63], v[8:11], v[12:15]
	s_waitcnt vmcnt(11)
	v_mfma_f32_16x16x32_bf16 v[12:15], v[64:67], v[4:7], v[16:19]
	s_waitcnt vmcnt(7)
	v_mfma_f32_16x16x32_bf16 v[28:31], v[80:83], v[0:3], v[12:15]
	v_mfma_f32_16x16x32_bf16 v[16:19], v[68:71], v[4:7], v[24:27]
	s_nop 4
	v_add_f32_e32 v12, v216, v217
	v_div_scale_f32 v13, s[6:7], v12, v12, 1.0
	v_rcp_f32_e32 v14, v13
	v_mfma_f32_16x16x32_bf16 v[24:27], v[76:79], v[4:7], v[8:11]
	v_fma_f32 v15, -v13, v14, 1.0
	v_fmac_f32_e32 v14, v15, v14
	v_div_scale_f32 v15, vcc, 1.0, v12, 1.0
	s_waitcnt vmcnt(6)
	v_mfma_f32_16x16x32_bf16 v[8:11], v[84:87], v[0:3], v[16:19]
	s_nop 2
	v_mul_f32_e32 v16, v15, v14
	v_fma_f32 v17, -v13, v16, v15
	v_fmac_f32_e32 v16, v17, v14
	v_fma_f32 v13, -v13, v16, v15
	v_div_fmas_f32 v13, v13, v14, v16
	v_lshl_add_u64 v[14:15], v[136:137], 0, v[144:145]
	v_add_co_u32_e32 v16, vcc, s51, v14
	v_div_fixup_f32 v12, v13, v12, 1.0
	s_nop 0
	v_addc_co_u32_e32 v17, vcc, 0, v15, vcc
	s_nop 0
	v_mfma_f32_16x16x32_bf16 v[20:23], v[72:75], v[4:7], v[20:23]
	v_add_co_u32_e32 v14, vcc, s46, v14
	s_waitcnt vmcnt(3)
	v_mov_b32_e32 v16, v232
	v_mov_b32_e32 v17, v233
	v_lshlrev_b32_e32 v18, 16, v16
	v_mul_f32_e32 v13, 0xbfb8aa3b, v18
	v_exp_f32_e32 v13, v13
	v_and_b32_e32 v19, 0xffff0000, v16
	v_mfma_f32_16x16x32_bf16 v[4:7], v[88:91], v[0:3], v[20:23]
	v_addc_co_u32_e32 v15, vcc, 0, v15, vcc
	v_add_f32_e32 v13, 1.0, v13
	s_nop 0
	v_rcp_f32_e32 v20, v13
	v_pk_mul_f32 v[22:23], v[28:29], v[12:13] op_sel_hi:[1,0]
	v_mul_f32_e32 v13, 0xbfb8aa3b, v19
	v_exp_f32_e32 v13, v13
	v_mfma_f32_16x16x32_bf16 v[0:3], v[92:95], v[0:3], v[24:27]
	v_add_f32_e32 v13, 1.0, v13
	v_rcp_f32_e32 v21, v13
	s_nop 0
	v_pk_mul_f32 v[18:19], v[20:21], v[18:19]
	s_nop 0
	v_pk_mul_f32 v[18:19], v[22:23], v[18:19]
	s_nop 0
	v_cvt_pk_bf16_f32 v16, v18, v19
	v_lshlrev_b32_e32 v18, 16, v17
	v_mul_f32_e32 v13, 0xbfb8aa3b, v18
	v_exp_f32_e32 v13, v13
	v_and_b32_e32 v19, 0xffff0000, v17
	v_add_f32_e32 v13, 1.0, v13
	v_rcp_f32_e32 v20, v13
	v_pk_mul_f32 v[22:23], v[30:31], v[12:13] op_sel_hi:[1,0]
	v_mul_f32_e32 v13, 0xbfb8aa3b, v19
	v_exp_f32_e32 v13, v13
	s_nop 0
	v_add_f32_e32 v13, 1.0, v13
	v_rcp_f32_e32 v21, v13
	s_nop 0
	v_pk_mul_f32 v[18:19], v[20:21], v[18:19]
	s_nop 0
	v_pk_mul_f32 v[18:19], v[22:23], v[18:19]
	s_nop 0
	v_cvt_pk_bf16_f32 v17, v18, v19
	global_store_dwordx2 v[14:15], v[16:17], off
	v_lshl_add_u64 v[14:15], v[136:137], 0, v[142:143]
	v_add_co_u32_e32 v16, vcc, s51, v14
	s_nop 1
	v_addc_co_u32_e32 v17, vcc, 0, v15, vcc
	s_nop 0
	s_waitcnt vmcnt(3)
; __device__ __forceinline__ unsigned pk2(float lo, float hi) { const f32x2 v = {lo, hi}; const bf16x2_t b = __builtin_convertvector(v, bf16x2_t); return __builtin_bit_cast(unsigned, b); }
; __device__ __forceinline__ float silu_f(float v) { return v * __builtin_amdgcn_rcpf(1.f + __expf(-v)); }
; __device__ __forceinline__ void phase_attn(const Args& a, unsigned char* smem, int tid, int lane, int wave, bf16_t* Yout) {
;     ...
;             const float inv = 1.f / l;
; #pragma unroll
;             for (int mt = 0; mt < 4; ++mt) {
;                 const size_t off = qrow * 1024 + h * 64 + mt * 16 + 4 * g;
;                 const u32x2 z = *(const u32x2*)(AZ + off);
;                 u32x2 w; w.x = pk2(o[mt][0] * inv * silu_f(bflo(z.x)), o[mt][1] * inv * silu_f(bfhi(z.x)));
;                 w.y = pk2(o[mt][2] * inv * silu_f(bflo(z.y)), o[mt][3] * inv * silu_f(bfhi(z.y)));
;                 *(u32x2*)(Yout + off) = w;
;             }
	v_mov_b32_e32 v16, v234
	v_mov_b32_e32 v17, v235
	v_lshlrev_b32_e32 v18, 16, v16
	v_mul_f32_e32 v13, 0xbfb8aa3b, v18
	v_exp_f32_e32 v13, v13
	v_and_b32_e32 v19, 0xffff0000, v16
	v_lshlrev_b32_e32 v16, 16, v17
	v_and_b32_e32 v17, 0xffff0000, v17
	v_add_f32_e32 v13, 1.0, v13
	v_rcp_f32_e32 v20, v13
	v_pk_mul_f32 v[8:9], v[8:9], v[12:13] op_sel_hi:[1,0]
	v_mul_f32_e32 v13, 0xbfb8aa3b, v19
	v_exp_f32_e32 v13, v13
	s_nop 0
	v_add_f32_e32 v13, 1.0, v13
	v_rcp_f32_e32 v21, v13
	v_pk_mul_f32 v[10:11], v[10:11], v[12:13] op_sel_hi:[1,0]
	v_pk_mul_f32 v[4:5], v[4:5], v[12:13] op_sel_hi:[1,0]
	v_pk_mul_f32 v[6:7], v[6:7], v[12:13] op_sel_hi:[1,0]
	v_pk_mul_f32 v[18:19], v[20:21], v[18:19]
	v_pk_mul_f32 v[0:1], v[0:1], v[12:13] op_sel_hi:[1,0]
	v_pk_mul_f32 v[8:9], v[8:9], v[18:19]
	v_pk_mul_f32 v[2:3], v[2:3], v[12:13] op_sel_hi:[1,0]
	v_cvt_pk_bf16_f32 v8, v8, v9
	v_mul_f32_e32 v9, 0xbfb8aa3b, v16
	v_exp_f32_e32 v9, v9
	s_nop 0
	v_add_f32_e32 v9, 1.0, v9
	v_rcp_f32_e32 v18, v9
	v_mul_f32_e32 v9, 0xbfb8aa3b, v17
	v_exp_f32_e32 v9, v9
	s_nop 0
	v_add_f32_e32 v9, 1.0, v9
	v_rcp_f32_e32 v19, v9
	s_nop 0
	v_pk_mul_f32 v[16:17], v[18:19], v[16:17]
	s_nop 0
	v_pk_mul_f32 v[10:11], v[10:11], v[16:17]
	s_nop 0
	v_cvt_pk_bf16_f32 v9, v10, v11
	v_add_co_u32_e32 v10, vcc, s46, v14
	s_nop 1
	v_addc_co_u32_e32 v11, vcc, 0, v15, vcc
	global_store_dwordx2 v[10:11], v[8:9], off
	v_lshl_add_u64 v[8:9], v[136:137], 0, v[140:141]
	v_add_co_u32_e32 v10, vcc, s51, v8
	s_nop 1
	v_addc_co_u32_e32 v11, vcc, 0, v9, vcc
	s_nop 0
	s_waitcnt vmcnt(3)
	v_mov_b32_e32 v10, v236
	v_mov_b32_e32 v11, v237
	v_lshlrev_b32_e32 v14, 16, v10
	v_and_b32_e32 v15, 0xffff0000, v10
	v_mul_f32_e32 v10, 0xbfb8aa3b, v14
	v_exp_f32_e32 v10, v10
	s_nop 0
	v_add_f32_e32 v10, 1.0, v10
	v_rcp_f32_e32 v16, v10
	v_mul_f32_e32 v10, 0xbfb8aa3b, v15
	v_exp_f32_e32 v10, v10
	s_nop 0
	v_add_f32_e32 v10, 1.0, v10
	v_rcp_f32_e32 v17, v10
	v_lshlrev_b32_e32 v10, 16, v11
	v_and_b32_e32 v11, 0xffff0000, v11
	v_pk_mul_f32 v[14:15], v[16:17], v[14:15]
	s_nop 0
	v_pk_mul_f32 v[4:5], v[4:5], v[14:15]
	s_nop 0
	v_cvt_pk_bf16_f32 v4, v4, v5
	v_mul_f32_e32 v5, 0xbfb8aa3b, v10
	v_exp_f32_e32 v5, v5
	s_nop 0
	v_add_f32_e32 v5, 1.0, v5
	v_rcp_f32_e32 v14, v5
	v_mul_f32_e32 v5, 0xbfb8aa3b, v11
	v_exp_f32_e32 v5, v5
	s_nop 0
	v_add_f32_e32 v5, 1.0, v5
	v_rcp_f32_e32 v15, v5
	s_nop 0
	v_pk_mul_f32 v[10:11], v[14:15], v[10:11]
	s_nop 0
	v_pk_mul_f32 v[6:7], v[6:7], v[10:11]
	s_nop 0
	v_cvt_pk_bf16_f32 v5, v6, v7
	v_add_co_u32_e32 v6, vcc, s46, v8
	s_nop 1
	v_addc_co_u32_e32 v7, vcc, 0, v9, vcc
	global_store_dwordx2 v[6:7], v[4:5], off
	v_lshl_add_u64 v[4:5], v[136:137], 0, v[138:139]
	v_add_co_u32_e32 v6, vcc, s51, v4
	v_lshl_add_u64 v[136:137], v[136:137], 0, s[20:21]
	s_nop 0
	v_addc_co_u32_e32 v7, vcc, 0, v5, vcc
	s_nop 0
	s_waitcnt vmcnt(3)
	v_mov_b32_e32 v6, v238
	v_mov_b32_e32 v7, v239
	v_lshlrev_b32_e32 v8, 16, v6
	v_and_b32_e32 v9, 0xffff0000, v6
	v_mul_f32_e32 v6, 0xbfb8aa3b, v8
	v_exp_f32_e32 v6, v6
	s_nop 0
	v_add_f32_e32 v6, 1.0, v6
	v_rcp_f32_e32 v10, v6
	v_mul_f32_e32 v6, 0xbfb8aa3b, v9
	v_exp_f32_e32 v6, v6
	s_nop 0
	v_add_f32_e32 v6, 1.0, v6
	v_rcp_f32_e32 v11, v6
	v_lshlrev_b32_e32 v6, 16, v7
	v_and_b32_e32 v7, 0xffff0000, v7
	v_pk_mul_f32 v[8:9], v[10:11], v[8:9]
	s_nop 0
	v_pk_mul_f32 v[0:1], v[0:1], v[8:9]
	s_nop 0
	v_cvt_pk_bf16_f32 v0, v0, v1
	v_mul_f32_e32 v1, 0xbfb8aa3b, v6
	v_exp_f32_e32 v1, v1
	s_nop 0
	v_add_f32_e32 v1, 1.0, v1
	v_rcp_f32_e32 v8, v1
	v_mul_f32_e32 v1, 0xbfb8aa3b, v7
	v_exp_f32_e32 v1, v1
	s_nop 0
	v_add_f32_e32 v1, 1.0, v1
	v_rcp_f32_e32 v9, v1
	s_nop 0
	v_pk_mul_f32 v[6:7], v[8:9], v[6:7]
	s_nop 0
	v_pk_mul_f32 v[2:3], v[2:3], v[6:7]
	s_nop 0
	v_cvt_pk_bf16_f32 v1, v2, v3
	v_add_co_u32_e32 v2, vcc, 0x100000, v4
	s_nop 1
	v_addc_co_u32_e32 v3, vcc, 0, v5, vcc
	global_store_dwordx2 v[2:3], v[0:1], off
	s_cbranch_scc1 .LBB0_329
